# select fast path instruction selection: SDWA byte compare for the level-1 candidate test, plain compare at level 2 (no v_and), clamp after the key conversion dropped
# speedup vs baseline: 1.0010x; 1.0010x over previous
.Lsel_f2_7:
.Lsel_f2_done:
	v_sub_f32_e32 v199, v2, v234
	v_sub_f32_e32 v200, v3, v234
	v_sub_f32_e32 v201, v4, v234
	v_sub_f32_e32 v202, v5, v234
	v_mul_f32_e32 v199, v199, v236
	v_mul_f32_e32 v200, v200, v236
	v_mul_f32_e32 v201, v201, v236
	v_mul_f32_e32 v202, v202, v236
	v_cvt_u32_f32_e32 v199, v199
	v_cvt_u32_f32_e32 v200, v200
	v_cvt_u32_f32_e32 v201, v201
	v_cvt_u32_f32_e32 v202, v202
	v_lshrrev_b32_e32 v186, 8, v199
	v_lshrrev_b32_e32 v187, 8, v200
	v_lshrrev_b32_e32 v192, 8, v201
	v_lshrrev_b32_e32 v193, 8, v202
	v_lshl_add_u32 v186, v186, 2, v232
	v_lshl_add_u32 v187, v187, 2, v232
	v_lshl_add_u32 v192, v192, 2, v232
	v_lshl_add_u32 v193, v193, 2, v232
	ds_add_u32 v186, v233
	ds_add_u32 v187, v233
	ds_add_u32 v192, v233
	ds_add_u32 v193, v233
	v_sub_f32_e32 v203, v6, v234
	v_sub_f32_e32 v204, v7, v234
	v_sub_f32_e32 v205, v8, v234
	v_sub_f32_e32 v206, v9, v234
	v_mul_f32_e32 v203, v203, v236
	v_mul_f32_e32 v204, v204, v236
	v_mul_f32_e32 v205, v205, v236
	v_mul_f32_e32 v206, v206, v236
	v_cvt_u32_f32_e32 v203, v203
	v_cvt_u32_f32_e32 v204, v204
	v_cvt_u32_f32_e32 v205, v205
	v_cvt_u32_f32_e32 v206, v206
	v_lshrrev_b32_e32 v186, 8, v203
	v_lshrrev_b32_e32 v187, 8, v204
	v_lshrrev_b32_e32 v192, 8, v205
	v_lshrrev_b32_e32 v193, 8, v206
	v_lshl_add_u32 v186, v186, 2, v232
	v_lshl_add_u32 v187, v187, 2, v232
	v_lshl_add_u32 v192, v192, 2, v232
	v_lshl_add_u32 v193, v193, 2, v232
	ds_add_u32 v186, v233
	ds_add_u32 v187, v233
	ds_add_u32 v192, v233
	ds_add_u32 v193, v233
	s_cmpk_lt_u32 s6, 2
	s_cbranch_scc1 .Lsel_B_done
	v_sub_f32_e32 v207, v10, v234
	v_sub_f32_e32 v208, v11, v234
	v_sub_f32_e32 v209, v12, v234
	v_sub_f32_e32 v210, v13, v234
	v_mul_f32_e32 v207, v207, v236
	v_mul_f32_e32 v208, v208, v236
	v_mul_f32_e32 v209, v209, v236
	v_mul_f32_e32 v210, v210, v236
	v_cvt_u32_f32_e32 v207, v207
	v_cvt_u32_f32_e32 v208, v208
	v_cvt_u32_f32_e32 v209, v209
	v_cvt_u32_f32_e32 v210, v210
	v_lshrrev_b32_e32 v186, 8, v207
	v_lshrrev_b32_e32 v187, 8, v208
	v_lshrrev_b32_e32 v192, 8, v209
	v_lshrrev_b32_e32 v193, 8, v210
	v_lshl_add_u32 v186, v186, 2, v232
	v_lshl_add_u32 v187, v187, 2, v232
	v_lshl_add_u32 v192, v192, 2, v232
	v_lshl_add_u32 v193, v193, 2, v232
	ds_add_u32 v186, v233
	ds_add_u32 v187, v233
	ds_add_u32 v192, v233
	ds_add_u32 v193, v233
	s_cmpk_lt_u32 s6, 3
	s_cbranch_scc1 .Lsel_B_done
	v_sub_f32_e32 v211, v14, v234
	v_sub_f32_e32 v212, v15, v234
	v_sub_f32_e32 v213, v16, v234
	v_sub_f32_e32 v214, v17, v234
	v_mul_f32_e32 v211, v211, v236
	v_mul_f32_e32 v212, v212, v236
	v_mul_f32_e32 v213, v213, v236
	v_mul_f32_e32 v214, v214, v236
	v_cvt_u32_f32_e32 v211, v211
	v_cvt_u32_f32_e32 v212, v212
	v_cvt_u32_f32_e32 v213, v213
	v_cvt_u32_f32_e32 v214, v214
	v_lshrrev_b32_e32 v186, 8, v211
	v_lshrrev_b32_e32 v187, 8, v212
	v_lshrrev_b32_e32 v192, 8, v213
	v_lshrrev_b32_e32 v193, 8, v214
	v_lshl_add_u32 v186, v186, 2, v232
	v_lshl_add_u32 v187, v187, 2, v232
	v_lshl_add_u32 v192, v192, 2, v232
	v_lshl_add_u32 v193, v193, 2, v232
	ds_add_u32 v186, v233
	ds_add_u32 v187, v233
	ds_add_u32 v192, v233
	ds_add_u32 v193, v233
	s_cmpk_lt_u32 s6, 4
	s_cbranch_scc1 .Lsel_B_done
	v_sub_f32_e32 v215, v18, v234
	v_sub_f32_e32 v216, v19, v234
	v_sub_f32_e32 v217, v20, v234
	v_sub_f32_e32 v218, v21, v234
	v_mul_f32_e32 v215, v215, v236
	v_mul_f32_e32 v216, v216, v236
	v_mul_f32_e32 v217, v217, v236
	v_mul_f32_e32 v218, v218, v236
	v_cvt_u32_f32_e32 v215, v215
	v_cvt_u32_f32_e32 v216, v216
	v_cvt_u32_f32_e32 v217, v217
	v_cvt_u32_f32_e32 v218, v218
	v_lshrrev_b32_e32 v186, 8, v215
	v_lshrrev_b32_e32 v187, 8, v216
	v_lshrrev_b32_e32 v192, 8, v217
	v_lshrrev_b32_e32 v193, 8, v218
	v_lshl_add_u32 v186, v186, 2, v232
	v_lshl_add_u32 v187, v187, 2, v232
	v_lshl_add_u32 v192, v192, 2, v232
	v_lshl_add_u32 v193, v193, 2, v232
	ds_add_u32 v186, v233
	ds_add_u32 v187, v233
	ds_add_u32 v192, v233
	ds_add_u32 v193, v233
	s_cmpk_lt_u32 s6, 5
	s_cbranch_scc1 .Lsel_B_done
	v_sub_f32_e32 v219, v22, v234
	v_sub_f32_e32 v220, v23, v234
	v_sub_f32_e32 v221, v24, v234
	v_sub_f32_e32 v222, v25, v234
	v_mul_f32_e32 v219, v219, v236
	v_mul_f32_e32 v220, v220, v236
	v_mul_f32_e32 v221, v221, v236
	v_mul_f32_e32 v222, v222, v236
	v_cvt_u32_f32_e32 v219, v219
	v_cvt_u32_f32_e32 v220, v220
	v_cvt_u32_f32_e32 v221, v221
	v_cvt_u32_f32_e32 v222, v222
	v_lshrrev_b32_e32 v186, 8, v219
	v_lshrrev_b32_e32 v187, 8, v220
	v_lshrrev_b32_e32 v192, 8, v221
	v_lshrrev_b32_e32 v193, 8, v222
	v_lshl_add_u32 v186, v186, 2, v232
	v_lshl_add_u32 v187, v187, 2, v232
	v_lshl_add_u32 v192, v192, 2, v232
	v_lshl_add_u32 v193, v193, 2, v232
	ds_add_u32 v186, v233
	ds_add_u32 v187, v233
	ds_add_u32 v192, v233
	ds_add_u32 v193, v233
	s_cmpk_lt_u32 s6, 6
	s_cbranch_scc1 .Lsel_B_done
	v_sub_f32_e32 v223, v26, v234
	v_sub_f32_e32 v224, v27, v234
	v_sub_f32_e32 v225, v28, v234
	v_sub_f32_e32 v226, v29, v234
	v_mul_f32_e32 v223, v223, v236
	v_mul_f32_e32 v224, v224, v236
	v_mul_f32_e32 v225, v225, v236
	v_mul_f32_e32 v226, v226, v236
	v_cvt_u32_f32_e32 v223, v223
	v_cvt_u32_f32_e32 v224, v224
	v_cvt_u32_f32_e32 v225, v225
	v_cvt_u32_f32_e32 v226, v226
	v_lshrrev_b32_e32 v186, 8, v223
	v_lshrrev_b32_e32 v187, 8, v224
	v_lshrrev_b32_e32 v192, 8, v225
	v_lshrrev_b32_e32 v193, 8, v226
	v_lshl_add_u32 v186, v186, 2, v232
	v_lshl_add_u32 v187, v187, 2, v232
	v_lshl_add_u32 v192, v192, 2, v232
	v_lshl_add_u32 v193, v193, 2, v232
	ds_add_u32 v186, v233
	ds_add_u32 v187, v233
	ds_add_u32 v192, v233
	ds_add_u32 v193, v233
	s_cmpk_lt_u32 s6, 7
	s_cbranch_scc1 .Lsel_B_done
	v_sub_f32_e32 v227, v30, v234
	v_sub_f32_e32 v228, v31, v234
	v_sub_f32_e32 v229, v32, v234
	v_sub_f32_e32 v230, v33, v234
	v_mul_f32_e32 v227, v227, v236
	v_mul_f32_e32 v228, v228, v236
	v_mul_f32_e32 v229, v229, v236
	v_mul_f32_e32 v230, v230, v236
	v_cvt_u32_f32_e32 v227, v227
	v_cvt_u32_f32_e32 v228, v228
	v_cvt_u32_f32_e32 v229, v229
	v_cvt_u32_f32_e32 v230, v230
	v_lshrrev_b32_e32 v186, 8, v227
	v_lshrrev_b32_e32 v187, 8, v228
	v_lshrrev_b32_e32 v192, 8, v229
	v_lshrrev_b32_e32 v193, 8, v230
	v_lshl_add_u32 v186, v186, 2, v232
	v_lshl_add_u32 v187, v187, 2, v232
	v_lshl_add_u32 v192, v192, 2, v232
	v_lshl_add_u32 v193, v193, 2, v232
	ds_add_u32 v186, v233
	ds_add_u32 v187, v233
	ds_add_u32 v192, v233
	ds_add_u32 v193, v233

.Lsel_C_found:
	s_sub_i32 s81, s81, s2
	s_cmp_eq_u32 s5, 2
	s_cbranch_scc1 .Lsel_C2
	s_cmp_eq_u32 s80, 0
	s_cbranch_scc1 .Lsel_bail
	s_lshl_b32 s83, s80, 8
	s_mov_b32 s76, s80
	v_mov_b32_e32 v195, 0
	v_mov_b32_e32 v196, 0
	v_cmp_eq_u32_sdwa vcc, v199, s76 src0_sel:BYTE_1 src1_sel:DWORD
	v_cmp_eq_u32_sdwa s[0:1], v200, s76 src0_sel:BYTE_1 src1_sel:DWORD
	v_cmp_eq_u32_sdwa s[2:3], v201, s76 src0_sel:BYTE_1 src1_sel:DWORD
	v_cmp_eq_u32_sdwa s[72:73], v202, s76 src0_sel:BYTE_1 src1_sel:DWORD
	v_addc_co_u32_e64 v195, vcc, 0, v195, vcc
	v_addc_co_u32_e64 v196, s[0:1], 0, v196, s[0:1]
	v_addc_co_u32_e64 v195, s[2:3], 0, v195, s[2:3]
	v_addc_co_u32_e64 v196, s[72:73], 0, v196, s[72:73]
	v_cmp_eq_u32_sdwa vcc, v203, s76 src0_sel:BYTE_1 src1_sel:DWORD
	v_cmp_eq_u32_sdwa s[0:1], v204, s76 src0_sel:BYTE_1 src1_sel:DWORD
	v_cmp_eq_u32_sdwa s[2:3], v205, s76 src0_sel:BYTE_1 src1_sel:DWORD
	v_cmp_eq_u32_sdwa s[72:73], v206, s76 src0_sel:BYTE_1 src1_sel:DWORD
	v_addc_co_u32_e64 v195, vcc, 0, v195, vcc
	v_addc_co_u32_e64 v196, s[0:1], 0, v196, s[0:1]
	v_addc_co_u32_e64 v195, s[2:3], 0, v195, s[2:3]
	v_addc_co_u32_e64 v196, s[72:73], 0, v196, s[72:73]
	s_cmpk_lt_u32 s6, 2
	s_cbranch_scc1 .Lsel_D1_done
	v_cmp_eq_u32_sdwa vcc, v207, s76 src0_sel:BYTE_1 src1_sel:DWORD
	v_cmp_eq_u32_sdwa s[0:1], v208, s76 src0_sel:BYTE_1 src1_sel:DWORD
	v_cmp_eq_u32_sdwa s[2:3], v209, s76 src0_sel:BYTE_1 src1_sel:DWORD
	v_cmp_eq_u32_sdwa s[72:73], v210, s76 src0_sel:BYTE_1 src1_sel:DWORD
	v_addc_co_u32_e64 v195, vcc, 0, v195, vcc
	v_addc_co_u32_e64 v196, s[0:1], 0, v196, s[0:1]
	v_addc_co_u32_e64 v195, s[2:3], 0, v195, s[2:3]
	v_addc_co_u32_e64 v196, s[72:73], 0, v196, s[72:73]
	s_cmpk_lt_u32 s6, 3
	s_cbranch_scc1 .Lsel_D1_done
	v_cmp_eq_u32_sdwa vcc, v211, s76 src0_sel:BYTE_1 src1_sel:DWORD
	v_cmp_eq_u32_sdwa s[0:1], v212, s76 src0_sel:BYTE_1 src1_sel:DWORD
	v_cmp_eq_u32_sdwa s[2:3], v213, s76 src0_sel:BYTE_1 src1_sel:DWORD
	v_cmp_eq_u32_sdwa s[72:73], v214, s76 src0_sel:BYTE_1 src1_sel:DWORD
	v_addc_co_u32_e64 v195, vcc, 0, v195, vcc
	v_addc_co_u32_e64 v196, s[0:1], 0, v196, s[0:1]
	v_addc_co_u32_e64 v195, s[2:3], 0, v195, s[2:3]
	v_addc_co_u32_e64 v196, s[72:73], 0, v196, s[72:73]
	s_cmpk_lt_u32 s6, 4
	s_cbranch_scc1 .Lsel_D1_done
	v_cmp_eq_u32_sdwa vcc, v215, s76 src0_sel:BYTE_1 src1_sel:DWORD
	v_cmp_eq_u32_sdwa s[0:1], v216, s76 src0_sel:BYTE_1 src1_sel:DWORD
	v_cmp_eq_u32_sdwa s[2:3], v217, s76 src0_sel:BYTE_1 src1_sel:DWORD
	v_cmp_eq_u32_sdwa s[72:73], v218, s76 src0_sel:BYTE_1 src1_sel:DWORD
	v_addc_co_u32_e64 v195, vcc, 0, v195, vcc
	v_addc_co_u32_e64 v196, s[0:1], 0, v196, s[0:1]
	v_addc_co_u32_e64 v195, s[2:3], 0, v195, s[2:3]
	v_addc_co_u32_e64 v196, s[72:73], 0, v196, s[72:73]
	s_cmpk_lt_u32 s6, 5
	s_cbranch_scc1 .Lsel_D1_done
	v_cmp_eq_u32_sdwa vcc, v219, s76 src0_sel:BYTE_1 src1_sel:DWORD
	v_cmp_eq_u32_sdwa s[0:1], v220, s76 src0_sel:BYTE_1 src1_sel:DWORD
	v_cmp_eq_u32_sdwa s[2:3], v221, s76 src0_sel:BYTE_1 src1_sel:DWORD
	v_cmp_eq_u32_sdwa s[72:73], v222, s76 src0_sel:BYTE_1 src1_sel:DWORD
	v_addc_co_u32_e64 v195, vcc, 0, v195, vcc
	v_addc_co_u32_e64 v196, s[0:1], 0, v196, s[0:1]
	v_addc_co_u32_e64 v195, s[2:3], 0, v195, s[2:3]
	v_addc_co_u32_e64 v196, s[72:73], 0, v196, s[72:73]
	s_cmpk_lt_u32 s6, 6
	s_cbranch_scc1 .Lsel_D1_done
	v_cmp_eq_u32_sdwa vcc, v223, s76 src0_sel:BYTE_1 src1_sel:DWORD
	v_cmp_eq_u32_sdwa s[0:1], v224, s76 src0_sel:BYTE_1 src1_sel:DWORD
	v_cmp_eq_u32_sdwa s[2:3], v225, s76 src0_sel:BYTE_1 src1_sel:DWORD
	v_cmp_eq_u32_sdwa s[72:73], v226, s76 src0_sel:BYTE_1 src1_sel:DWORD
	v_addc_co_u32_e64 v195, vcc, 0, v195, vcc
	v_addc_co_u32_e64 v196, s[0:1], 0, v196, s[0:1]
	v_addc_co_u32_e64 v195, s[2:3], 0, v195, s[2:3]
	v_addc_co_u32_e64 v196, s[72:73], 0, v196, s[72:73]
	s_cmpk_lt_u32 s6, 7
	s_cbranch_scc1 .Lsel_D1_done
	v_cmp_eq_u32_sdwa vcc, v227, s76 src0_sel:BYTE_1 src1_sel:DWORD
	v_cmp_eq_u32_sdwa s[0:1], v228, s76 src0_sel:BYTE_1 src1_sel:DWORD
	v_cmp_eq_u32_sdwa s[2:3], v229, s76 src0_sel:BYTE_1 src1_sel:DWORD
	v_cmp_eq_u32_sdwa s[72:73], v230, s76 src0_sel:BYTE_1 src1_sel:DWORD
	v_addc_co_u32_e64 v195, vcc, 0, v195, vcc
	v_addc_co_u32_e64 v196, s[0:1], 0, v196, s[0:1]
	v_addc_co_u32_e64 v195, s[2:3], 0, v195, s[2:3]
	v_addc_co_u32_e64 v196, s[72:73], 0, v196, s[72:73]

.Lsel_D1_ne:
	s_cmpk_le_u32 s82, 64
	s_cbranch_scc0 .Lsel_lvl2
	s_or_b32 s80, s83, 0xff
	s_and_b32 s4, s28, 7
	s_lshl_b32 s4, s4, 13
	s_add_i32 s4, s4, 0xc800
	s_nop 1
	v_lshl_add_u32 v240, v239, 3, s4
	v_cmp_eq_u32_sdwa s[0:1], v199, s76 src0_sel:BYTE_1 src1_sel:DWORD
	v_cmp_eq_u32_sdwa s[2:3], v200, s76 src0_sel:BYTE_1 src1_sel:DWORD
	v_cmp_eq_u32_sdwa s[72:73], v201, s76 src0_sel:BYTE_1 src1_sel:DWORD
	v_cmp_eq_u32_sdwa s[74:75], v202, s76 src0_sel:BYTE_1 src1_sel:DWORD
	v_add_u32_e32 v241, 0, v231
	v_add_u32_e32 v242, 1, v231
	v_add_u32_e32 v243, 2, v231
	v_add_u32_e32 v248, 3, v231
	s_mov_b64 exec, s[0:1]
	ds_write2_b32 v240, v241, v2 offset1:1
	v_add_u32_e32 v240, 8, v240
	s_mov_b64 exec, s[2:3]
	ds_write2_b32 v240, v242, v3 offset1:1
	v_add_u32_e32 v240, 8, v240
	s_mov_b64 exec, s[72:73]
	ds_write2_b32 v240, v243, v4 offset1:1
	v_add_u32_e32 v240, 8, v240
	s_mov_b64 exec, s[74:75]
	ds_write2_b32 v240, v248, v5 offset1:1
	v_add_u32_e32 v240, 8, v240
	s_mov_b64 exec, -1
	v_cmp_eq_u32_sdwa s[0:1], v203, s76 src0_sel:BYTE_1 src1_sel:DWORD
	v_cmp_eq_u32_sdwa s[2:3], v204, s76 src0_sel:BYTE_1 src1_sel:DWORD
	v_cmp_eq_u32_sdwa s[72:73], v205, s76 src0_sel:BYTE_1 src1_sel:DWORD
	v_cmp_eq_u32_sdwa s[74:75], v206, s76 src0_sel:BYTE_1 src1_sel:DWORD
	v_add_u32_e32 v241, 0x100, v231
	v_add_u32_e32 v242, 0x101, v231
	v_add_u32_e32 v243, 0x102, v231
	v_add_u32_e32 v248, 0x103, v231
	s_mov_b64 exec, s[0:1]
	ds_write2_b32 v240, v241, v6 offset1:1
	v_add_u32_e32 v240, 8, v240
	s_mov_b64 exec, s[2:3]
	ds_write2_b32 v240, v242, v7 offset1:1
	v_add_u32_e32 v240, 8, v240
	s_mov_b64 exec, s[72:73]
	ds_write2_b32 v240, v243, v8 offset1:1
	v_add_u32_e32 v240, 8, v240
	s_mov_b64 exec, s[74:75]
	ds_write2_b32 v240, v248, v9 offset1:1
	v_add_u32_e32 v240, 8, v240
	s_mov_b64 exec, -1
	s_cmpk_lt_u32 s6, 2
	s_cbranch_scc1 .Lsel_W1_done
	v_cmp_eq_u32_sdwa s[0:1], v207, s76 src0_sel:BYTE_1 src1_sel:DWORD
	v_cmp_eq_u32_sdwa s[2:3], v208, s76 src0_sel:BYTE_1 src1_sel:DWORD
	v_cmp_eq_u32_sdwa s[72:73], v209, s76 src0_sel:BYTE_1 src1_sel:DWORD
	v_cmp_eq_u32_sdwa s[74:75], v210, s76 src0_sel:BYTE_1 src1_sel:DWORD
	v_add_u32_e32 v241, 0x200, v231
	v_add_u32_e32 v242, 0x201, v231
	v_add_u32_e32 v243, 0x202, v231
	v_add_u32_e32 v248, 0x203, v231
	s_mov_b64 exec, s[0:1]
	ds_write2_b32 v240, v241, v10 offset1:1
	v_add_u32_e32 v240, 8, v240
	s_mov_b64 exec, s[2:3]
	ds_write2_b32 v240, v242, v11 offset1:1
	v_add_u32_e32 v240, 8, v240
	s_mov_b64 exec, s[72:73]
	ds_write2_b32 v240, v243, v12 offset1:1
	v_add_u32_e32 v240, 8, v240
	s_mov_b64 exec, s[74:75]
	ds_write2_b32 v240, v248, v13 offset1:1
	v_add_u32_e32 v240, 8, v240
	s_mov_b64 exec, -1
	s_cmpk_lt_u32 s6, 3
	s_cbranch_scc1 .Lsel_W1_done
	v_cmp_eq_u32_sdwa s[0:1], v211, s76 src0_sel:BYTE_1 src1_sel:DWORD
	v_cmp_eq_u32_sdwa s[2:3], v212, s76 src0_sel:BYTE_1 src1_sel:DWORD
	v_cmp_eq_u32_sdwa s[72:73], v213, s76 src0_sel:BYTE_1 src1_sel:DWORD
	v_cmp_eq_u32_sdwa s[74:75], v214, s76 src0_sel:BYTE_1 src1_sel:DWORD
	v_add_u32_e32 v241, 0x300, v231
	v_add_u32_e32 v242, 0x301, v231
	v_add_u32_e32 v243, 0x302, v231
	v_add_u32_e32 v248, 0x303, v231
	s_mov_b64 exec, s[0:1]
	ds_write2_b32 v240, v241, v14 offset1:1
	v_add_u32_e32 v240, 8, v240
	s_mov_b64 exec, s[2:3]
	ds_write2_b32 v240, v242, v15 offset1:1
	v_add_u32_e32 v240, 8, v240
	s_mov_b64 exec, s[72:73]
	ds_write2_b32 v240, v243, v16 offset1:1
	v_add_u32_e32 v240, 8, v240
	s_mov_b64 exec, s[74:75]
	ds_write2_b32 v240, v248, v17 offset1:1
	v_add_u32_e32 v240, 8, v240
	s_mov_b64 exec, -1
	s_cmpk_lt_u32 s6, 4
	s_cbranch_scc1 .Lsel_W1_done
	v_cmp_eq_u32_sdwa s[0:1], v215, s76 src0_sel:BYTE_1 src1_sel:DWORD
	v_cmp_eq_u32_sdwa s[2:3], v216, s76 src0_sel:BYTE_1 src1_sel:DWORD
	v_cmp_eq_u32_sdwa s[72:73], v217, s76 src0_sel:BYTE_1 src1_sel:DWORD
	v_cmp_eq_u32_sdwa s[74:75], v218, s76 src0_sel:BYTE_1 src1_sel:DWORD
	v_add_u32_e32 v241, 0x400, v231
	v_add_u32_e32 v242, 0x401, v231
	v_add_u32_e32 v243, 0x402, v231
	v_add_u32_e32 v248, 0x403, v231
	s_mov_b64 exec, s[0:1]
	ds_write2_b32 v240, v241, v18 offset1:1
	v_add_u32_e32 v240, 8, v240
	s_mov_b64 exec, s[2:3]
	ds_write2_b32 v240, v242, v19 offset1:1
	v_add_u32_e32 v240, 8, v240
	s_mov_b64 exec, s[72:73]
	ds_write2_b32 v240, v243, v20 offset1:1
	v_add_u32_e32 v240, 8, v240
	s_mov_b64 exec, s[74:75]
	ds_write2_b32 v240, v248, v21 offset1:1
	v_add_u32_e32 v240, 8, v240
	s_mov_b64 exec, -1
	s_cmpk_lt_u32 s6, 5
	s_cbranch_scc1 .Lsel_W1_done
	v_cmp_eq_u32_sdwa s[0:1], v219, s76 src0_sel:BYTE_1 src1_sel:DWORD
	v_cmp_eq_u32_sdwa s[2:3], v220, s76 src0_sel:BYTE_1 src1_sel:DWORD
	v_cmp_eq_u32_sdwa s[72:73], v221, s76 src0_sel:BYTE_1 src1_sel:DWORD
	v_cmp_eq_u32_sdwa s[74:75], v222, s76 src0_sel:BYTE_1 src1_sel:DWORD
	v_add_u32_e32 v241, 0x500, v231
	v_add_u32_e32 v242, 0x501, v231
	v_add_u32_e32 v243, 0x502, v231
	v_add_u32_e32 v248, 0x503, v231
	s_mov_b64 exec, s[0:1]
	ds_write2_b32 v240, v241, v22 offset1:1
	v_add_u32_e32 v240, 8, v240
	s_mov_b64 exec, s[2:3]
	ds_write2_b32 v240, v242, v23 offset1:1
	v_add_u32_e32 v240, 8, v240
	s_mov_b64 exec, s[72:73]
	ds_write2_b32 v240, v243, v24 offset1:1
	v_add_u32_e32 v240, 8, v240
	s_mov_b64 exec, s[74:75]
	ds_write2_b32 v240, v248, v25 offset1:1
	v_add_u32_e32 v240, 8, v240
	s_mov_b64 exec, -1
	s_cmpk_lt_u32 s6, 6
	s_cbranch_scc1 .Lsel_W1_done
	v_cmp_eq_u32_sdwa s[0:1], v223, s76 src0_sel:BYTE_1 src1_sel:DWORD
	v_cmp_eq_u32_sdwa s[2:3], v224, s76 src0_sel:BYTE_1 src1_sel:DWORD
	v_cmp_eq_u32_sdwa s[72:73], v225, s76 src0_sel:BYTE_1 src1_sel:DWORD
	v_cmp_eq_u32_sdwa s[74:75], v226, s76 src0_sel:BYTE_1 src1_sel:DWORD
	v_add_u32_e32 v241, 0x600, v231
	v_add_u32_e32 v242, 0x601, v231
	v_add_u32_e32 v243, 0x602, v231
	v_add_u32_e32 v248, 0x603, v231
	s_mov_b64 exec, s[0:1]
	ds_write2_b32 v240, v241, v26 offset1:1
	v_add_u32_e32 v240, 8, v240
	s_mov_b64 exec, s[2:3]
	ds_write2_b32 v240, v242, v27 offset1:1
	v_add_u32_e32 v240, 8, v240
	s_mov_b64 exec, s[72:73]
	ds_write2_b32 v240, v243, v28 offset1:1
	v_add_u32_e32 v240, 8, v240
	s_mov_b64 exec, s[74:75]
	ds_write2_b32 v240, v248, v29 offset1:1
	v_add_u32_e32 v240, 8, v240
	s_mov_b64 exec, -1
	s_cmpk_lt_u32 s6, 7
	s_cbranch_scc1 .Lsel_W1_done
	v_cmp_eq_u32_sdwa s[0:1], v227, s76 src0_sel:BYTE_1 src1_sel:DWORD
	v_cmp_eq_u32_sdwa s[2:3], v228, s76 src0_sel:BYTE_1 src1_sel:DWORD
	v_cmp_eq_u32_sdwa s[72:73], v229, s76 src0_sel:BYTE_1 src1_sel:DWORD
	v_cmp_eq_u32_sdwa s[74:75], v230, s76 src0_sel:BYTE_1 src1_sel:DWORD
	v_add_u32_e32 v241, 0x700, v231
	v_add_u32_e32 v242, 0x701, v231
	v_add_u32_e32 v243, 0x702, v231
	v_add_u32_e32 v248, 0x703, v231
	s_mov_b64 exec, s[0:1]
	ds_write2_b32 v240, v241, v30 offset1:1
	v_add_u32_e32 v240, 8, v240
	s_mov_b64 exec, s[2:3]
	ds_write2_b32 v240, v242, v31 offset1:1
	v_add_u32_e32 v240, 8, v240
	s_mov_b64 exec, s[72:73]
	ds_write2_b32 v240, v243, v32 offset1:1
	v_add_u32_e32 v240, 8, v240
	s_mov_b64 exec, s[74:75]
	ds_write2_b32 v240, v248, v33 offset1:1
	v_add_u32_e32 v240, 8, v240
	s_mov_b64 exec, -1

.Lsel_lvl2:
	s_mov_b32 s5, 2
	v_lshl_add_u32 v186, v198, 4, v232
	v_mov_b32_e32 v188, 0
	v_mov_b32_e32 v189, 0
	v_mov_b32_e32 v190, 0
	v_mov_b32_e32 v191, 0
	ds_write_b128 v186, v[188:191]
	v_cmp_eq_u32_sdwa s[0:1], v199, s76 src0_sel:BYTE_1 src1_sel:DWORD
	v_cmp_eq_u32_sdwa s[2:3], v200, s76 src0_sel:BYTE_1 src1_sel:DWORD
	v_cmp_eq_u32_sdwa s[72:73], v201, s76 src0_sel:BYTE_1 src1_sel:DWORD
	v_cmp_eq_u32_sdwa s[74:75], v202, s76 src0_sel:BYTE_1 src1_sel:DWORD
	v_and_b32_e32 v240, 0xff, v199
	v_and_b32_e32 v241, 0xff, v200
	v_and_b32_e32 v242, 0xff, v201
	v_and_b32_e32 v243, 0xff, v202
	v_lshl_add_u32 v240, v240, 2, v232
	v_lshl_add_u32 v241, v241, 2, v232
	v_lshl_add_u32 v242, v242, 2, v232
	v_lshl_add_u32 v243, v243, 2, v232
	s_mov_b64 exec, s[0:1]
	ds_add_u32 v240, v233
	s_mov_b64 exec, s[2:3]
	ds_add_u32 v241, v233
	s_mov_b64 exec, s[72:73]
	ds_add_u32 v242, v233
	s_mov_b64 exec, s[74:75]
	ds_add_u32 v243, v233
	s_mov_b64 exec, -1
	v_cmp_eq_u32_sdwa s[0:1], v203, s76 src0_sel:BYTE_1 src1_sel:DWORD
	v_cmp_eq_u32_sdwa s[2:3], v204, s76 src0_sel:BYTE_1 src1_sel:DWORD
	v_cmp_eq_u32_sdwa s[72:73], v205, s76 src0_sel:BYTE_1 src1_sel:DWORD
	v_cmp_eq_u32_sdwa s[74:75], v206, s76 src0_sel:BYTE_1 src1_sel:DWORD
	v_and_b32_e32 v240, 0xff, v203
	v_and_b32_e32 v241, 0xff, v204
	v_and_b32_e32 v242, 0xff, v205
	v_and_b32_e32 v243, 0xff, v206
	v_lshl_add_u32 v240, v240, 2, v232
	v_lshl_add_u32 v241, v241, 2, v232
	v_lshl_add_u32 v242, v242, 2, v232
	v_lshl_add_u32 v243, v243, 2, v232
	s_mov_b64 exec, s[0:1]
	ds_add_u32 v240, v233
	s_mov_b64 exec, s[2:3]
	ds_add_u32 v241, v233
	s_mov_b64 exec, s[72:73]
	ds_add_u32 v242, v233
	s_mov_b64 exec, s[74:75]
	ds_add_u32 v243, v233
	s_mov_b64 exec, -1
	s_cmpk_lt_u32 s6, 2
	s_cbranch_scc1 .Lsel_B2_done
	v_cmp_eq_u32_sdwa s[0:1], v207, s76 src0_sel:BYTE_1 src1_sel:DWORD
	v_cmp_eq_u32_sdwa s[2:3], v208, s76 src0_sel:BYTE_1 src1_sel:DWORD
	v_cmp_eq_u32_sdwa s[72:73], v209, s76 src0_sel:BYTE_1 src1_sel:DWORD
	v_cmp_eq_u32_sdwa s[74:75], v210, s76 src0_sel:BYTE_1 src1_sel:DWORD
	v_and_b32_e32 v240, 0xff, v207
	v_and_b32_e32 v241, 0xff, v208
	v_and_b32_e32 v242, 0xff, v209
	v_and_b32_e32 v243, 0xff, v210
	v_lshl_add_u32 v240, v240, 2, v232
	v_lshl_add_u32 v241, v241, 2, v232
	v_lshl_add_u32 v242, v242, 2, v232
	v_lshl_add_u32 v243, v243, 2, v232
	s_mov_b64 exec, s[0:1]
	ds_add_u32 v240, v233
	s_mov_b64 exec, s[2:3]
	ds_add_u32 v241, v233
	s_mov_b64 exec, s[72:73]
	ds_add_u32 v242, v233
	s_mov_b64 exec, s[74:75]
	ds_add_u32 v243, v233
	s_mov_b64 exec, -1
	s_cmpk_lt_u32 s6, 3
	s_cbranch_scc1 .Lsel_B2_done
	v_cmp_eq_u32_sdwa s[0:1], v211, s76 src0_sel:BYTE_1 src1_sel:DWORD
	v_cmp_eq_u32_sdwa s[2:3], v212, s76 src0_sel:BYTE_1 src1_sel:DWORD
	v_cmp_eq_u32_sdwa s[72:73], v213, s76 src0_sel:BYTE_1 src1_sel:DWORD
	v_cmp_eq_u32_sdwa s[74:75], v214, s76 src0_sel:BYTE_1 src1_sel:DWORD
	v_and_b32_e32 v240, 0xff, v211
	v_and_b32_e32 v241, 0xff, v212
	v_and_b32_e32 v242, 0xff, v213
	v_and_b32_e32 v243, 0xff, v214
	v_lshl_add_u32 v240, v240, 2, v232
	v_lshl_add_u32 v241, v241, 2, v232
	v_lshl_add_u32 v242, v242, 2, v232
	v_lshl_add_u32 v243, v243, 2, v232
	s_mov_b64 exec, s[0:1]
	ds_add_u32 v240, v233
	s_mov_b64 exec, s[2:3]
	ds_add_u32 v241, v233
	s_mov_b64 exec, s[72:73]
	ds_add_u32 v242, v233
	s_mov_b64 exec, s[74:75]
	ds_add_u32 v243, v233
	s_mov_b64 exec, -1
	s_cmpk_lt_u32 s6, 4
	s_cbranch_scc1 .Lsel_B2_done
	v_cmp_eq_u32_sdwa s[0:1], v215, s76 src0_sel:BYTE_1 src1_sel:DWORD
	v_cmp_eq_u32_sdwa s[2:3], v216, s76 src0_sel:BYTE_1 src1_sel:DWORD
	v_cmp_eq_u32_sdwa s[72:73], v217, s76 src0_sel:BYTE_1 src1_sel:DWORD
	v_cmp_eq_u32_sdwa s[74:75], v218, s76 src0_sel:BYTE_1 src1_sel:DWORD
	v_and_b32_e32 v240, 0xff, v215
	v_and_b32_e32 v241, 0xff, v216
	v_and_b32_e32 v242, 0xff, v217
	v_and_b32_e32 v243, 0xff, v218
	v_lshl_add_u32 v240, v240, 2, v232
	v_lshl_add_u32 v241, v241, 2, v232
	v_lshl_add_u32 v242, v242, 2, v232
	v_lshl_add_u32 v243, v243, 2, v232
	s_mov_b64 exec, s[0:1]
	ds_add_u32 v240, v233
	s_mov_b64 exec, s[2:3]
	ds_add_u32 v241, v233
	s_mov_b64 exec, s[72:73]
	ds_add_u32 v242, v233
	s_mov_b64 exec, s[74:75]
	ds_add_u32 v243, v233
	s_mov_b64 exec, -1
	s_cmpk_lt_u32 s6, 5
	s_cbranch_scc1 .Lsel_B2_done
	v_cmp_eq_u32_sdwa s[0:1], v219, s76 src0_sel:BYTE_1 src1_sel:DWORD
	v_cmp_eq_u32_sdwa s[2:3], v220, s76 src0_sel:BYTE_1 src1_sel:DWORD
	v_cmp_eq_u32_sdwa s[72:73], v221, s76 src0_sel:BYTE_1 src1_sel:DWORD
	v_cmp_eq_u32_sdwa s[74:75], v222, s76 src0_sel:BYTE_1 src1_sel:DWORD
	v_and_b32_e32 v240, 0xff, v219
	v_and_b32_e32 v241, 0xff, v220
	v_and_b32_e32 v242, 0xff, v221
	v_and_b32_e32 v243, 0xff, v222
	v_lshl_add_u32 v240, v240, 2, v232
	v_lshl_add_u32 v241, v241, 2, v232
	v_lshl_add_u32 v242, v242, 2, v232
	v_lshl_add_u32 v243, v243, 2, v232
	s_mov_b64 exec, s[0:1]
	ds_add_u32 v240, v233
	s_mov_b64 exec, s[2:3]
	ds_add_u32 v241, v233
	s_mov_b64 exec, s[72:73]
	ds_add_u32 v242, v233
	s_mov_b64 exec, s[74:75]
	ds_add_u32 v243, v233
	s_mov_b64 exec, -1
	s_cmpk_lt_u32 s6, 6
	s_cbranch_scc1 .Lsel_B2_done
	v_cmp_eq_u32_sdwa s[0:1], v223, s76 src0_sel:BYTE_1 src1_sel:DWORD
	v_cmp_eq_u32_sdwa s[2:3], v224, s76 src0_sel:BYTE_1 src1_sel:DWORD
	v_cmp_eq_u32_sdwa s[72:73], v225, s76 src0_sel:BYTE_1 src1_sel:DWORD
	v_cmp_eq_u32_sdwa s[74:75], v226, s76 src0_sel:BYTE_1 src1_sel:DWORD
	v_and_b32_e32 v240, 0xff, v223
	v_and_b32_e32 v241, 0xff, v224
	v_and_b32_e32 v242, 0xff, v225
	v_and_b32_e32 v243, 0xff, v226
	v_lshl_add_u32 v240, v240, 2, v232
	v_lshl_add_u32 v241, v241, 2, v232
	v_lshl_add_u32 v242, v242, 2, v232
	v_lshl_add_u32 v243, v243, 2, v232
	s_mov_b64 exec, s[0:1]
	ds_add_u32 v240, v233
	s_mov_b64 exec, s[2:3]
	ds_add_u32 v241, v233
	s_mov_b64 exec, s[72:73]
	ds_add_u32 v242, v233
	s_mov_b64 exec, s[74:75]
	ds_add_u32 v243, v233
	s_mov_b64 exec, -1
	s_cmpk_lt_u32 s6, 7
	s_cbranch_scc1 .Lsel_B2_done
	v_cmp_eq_u32_sdwa s[0:1], v227, s76 src0_sel:BYTE_1 src1_sel:DWORD
	v_cmp_eq_u32_sdwa s[2:3], v228, s76 src0_sel:BYTE_1 src1_sel:DWORD
	v_cmp_eq_u32_sdwa s[72:73], v229, s76 src0_sel:BYTE_1 src1_sel:DWORD
	v_cmp_eq_u32_sdwa s[74:75], v230, s76 src0_sel:BYTE_1 src1_sel:DWORD
	v_and_b32_e32 v240, 0xff, v227
	v_and_b32_e32 v241, 0xff, v228
	v_and_b32_e32 v242, 0xff, v229
	v_and_b32_e32 v243, 0xff, v230
	v_lshl_add_u32 v240, v240, 2, v232
	v_lshl_add_u32 v241, v241, 2, v232
	v_lshl_add_u32 v242, v242, 2, v232
	v_lshl_add_u32 v243, v243, 2, v232
	s_mov_b64 exec, s[0:1]
	ds_add_u32 v240, v233
	s_mov_b64 exec, s[2:3]
	ds_add_u32 v241, v233
	s_mov_b64 exec, s[72:73]
	ds_add_u32 v242, v233
	s_mov_b64 exec, s[74:75]
	ds_add_u32 v243, v233
	s_mov_b64 exec, -1

.Lsel_C2:
	s_or_b32 s83, s83, s80
	v_mov_b32_e32 v195, 0
	v_mov_b32_e32 v196, 0
	v_cmp_eq_u32_e64 vcc, s83, v199
	v_cmp_eq_u32_e64 s[0:1], s83, v200
	v_cmp_eq_u32_e64 s[2:3], s83, v201
	v_cmp_eq_u32_e64 s[72:73], s83, v202
	v_addc_co_u32_e64 v195, vcc, 0, v195, vcc
	v_addc_co_u32_e64 v196, s[0:1], 0, v196, s[0:1]
	v_addc_co_u32_e64 v195, s[2:3], 0, v195, s[2:3]
	v_addc_co_u32_e64 v196, s[72:73], 0, v196, s[72:73]
	v_cmp_eq_u32_e64 vcc, s83, v203
	v_cmp_eq_u32_e64 s[0:1], s83, v204
	v_cmp_eq_u32_e64 s[2:3], s83, v205
	v_cmp_eq_u32_e64 s[72:73], s83, v206
	v_addc_co_u32_e64 v195, vcc, 0, v195, vcc
	v_addc_co_u32_e64 v196, s[0:1], 0, v196, s[0:1]
	v_addc_co_u32_e64 v195, s[2:3], 0, v195, s[2:3]
	v_addc_co_u32_e64 v196, s[72:73], 0, v196, s[72:73]
	s_cmpk_lt_u32 s6, 2
	s_cbranch_scc1 .Lsel_D2_done
	v_cmp_eq_u32_e64 vcc, s83, v207
	v_cmp_eq_u32_e64 s[0:1], s83, v208
	v_cmp_eq_u32_e64 s[2:3], s83, v209
	v_cmp_eq_u32_e64 s[72:73], s83, v210
	v_addc_co_u32_e64 v195, vcc, 0, v195, vcc
	v_addc_co_u32_e64 v196, s[0:1], 0, v196, s[0:1]
	v_addc_co_u32_e64 v195, s[2:3], 0, v195, s[2:3]
	v_addc_co_u32_e64 v196, s[72:73], 0, v196, s[72:73]
	s_cmpk_lt_u32 s6, 3
	s_cbranch_scc1 .Lsel_D2_done
	v_cmp_eq_u32_e64 vcc, s83, v211
	v_cmp_eq_u32_e64 s[0:1], s83, v212
	v_cmp_eq_u32_e64 s[2:3], s83, v213
	v_cmp_eq_u32_e64 s[72:73], s83, v214
	v_addc_co_u32_e64 v195, vcc, 0, v195, vcc
	v_addc_co_u32_e64 v196, s[0:1], 0, v196, s[0:1]
	v_addc_co_u32_e64 v195, s[2:3], 0, v195, s[2:3]
	v_addc_co_u32_e64 v196, s[72:73], 0, v196, s[72:73]
	s_cmpk_lt_u32 s6, 4
	s_cbranch_scc1 .Lsel_D2_done
	v_cmp_eq_u32_e64 vcc, s83, v215
	v_cmp_eq_u32_e64 s[0:1], s83, v216
	v_cmp_eq_u32_e64 s[2:3], s83, v217
	v_cmp_eq_u32_e64 s[72:73], s83, v218
	v_addc_co_u32_e64 v195, vcc, 0, v195, vcc
	v_addc_co_u32_e64 v196, s[0:1], 0, v196, s[0:1]
	v_addc_co_u32_e64 v195, s[2:3], 0, v195, s[2:3]
	v_addc_co_u32_e64 v196, s[72:73], 0, v196, s[72:73]
	s_cmpk_lt_u32 s6, 5
	s_cbranch_scc1 .Lsel_D2_done
	v_cmp_eq_u32_e64 vcc, s83, v219
	v_cmp_eq_u32_e64 s[0:1], s83, v220
	v_cmp_eq_u32_e64 s[2:3], s83, v221
	v_cmp_eq_u32_e64 s[72:73], s83, v222
	v_addc_co_u32_e64 v195, vcc, 0, v195, vcc
	v_addc_co_u32_e64 v196, s[0:1], 0, v196, s[0:1]
	v_addc_co_u32_e64 v195, s[2:3], 0, v195, s[2:3]
	v_addc_co_u32_e64 v196, s[72:73], 0, v196, s[72:73]
	s_cmpk_lt_u32 s6, 6
	s_cbranch_scc1 .Lsel_D2_done
	v_cmp_eq_u32_e64 vcc, s83, v223
	v_cmp_eq_u32_e64 s[0:1], s83, v224
	v_cmp_eq_u32_e64 s[2:3], s83, v225
	v_cmp_eq_u32_e64 s[72:73], s83, v226
	v_addc_co_u32_e64 v195, vcc, 0, v195, vcc
	v_addc_co_u32_e64 v196, s[0:1], 0, v196, s[0:1]
	v_addc_co_u32_e64 v195, s[2:3], 0, v195, s[2:3]
	v_addc_co_u32_e64 v196, s[72:73], 0, v196, s[72:73]
	s_cmpk_lt_u32 s6, 7
	s_cbranch_scc1 .Lsel_D2_done
	v_cmp_eq_u32_e64 vcc, s83, v227
	v_cmp_eq_u32_e64 s[0:1], s83, v228
	v_cmp_eq_u32_e64 s[2:3], s83, v229
	v_cmp_eq_u32_e64 s[72:73], s83, v230
	v_addc_co_u32_e64 v195, vcc, 0, v195, vcc
	v_addc_co_u32_e64 v196, s[0:1], 0, v196, s[0:1]
	v_addc_co_u32_e64 v195, s[2:3], 0, v195, s[2:3]
	v_addc_co_u32_e64 v196, s[72:73], 0, v196, s[72:73]

.Lsel_D2_ne:
	s_cmpk_gt_u32 s82, 64
	s_cbranch_scc1 .Lsel_bail
	s_mov_b32 s80, s83
	s_and_b32 s4, s28, 7
	s_lshl_b32 s4, s4, 13
	s_add_i32 s4, s4, 0xc800
	s_nop 1
	v_lshl_add_u32 v240, v239, 3, s4
	v_cmp_eq_u32_e64 s[0:1], s83, v199
	v_cmp_eq_u32_e64 s[2:3], s83, v200
	v_cmp_eq_u32_e64 s[72:73], s83, v201
	v_cmp_eq_u32_e64 s[74:75], s83, v202
	v_add_u32_e32 v241, 0, v231
	v_add_u32_e32 v242, 1, v231
	v_add_u32_e32 v243, 2, v231
	v_add_u32_e32 v248, 3, v231
	s_mov_b64 exec, s[0:1]
	ds_write2_b32 v240, v241, v2 offset1:1
	v_add_u32_e32 v240, 8, v240
	s_mov_b64 exec, s[2:3]
	ds_write2_b32 v240, v242, v3 offset1:1
	v_add_u32_e32 v240, 8, v240
	s_mov_b64 exec, s[72:73]
	ds_write2_b32 v240, v243, v4 offset1:1
	v_add_u32_e32 v240, 8, v240
	s_mov_b64 exec, s[74:75]
	ds_write2_b32 v240, v248, v5 offset1:1
	v_add_u32_e32 v240, 8, v240
	s_mov_b64 exec, -1
	v_cmp_eq_u32_e64 s[0:1], s83, v203
	v_cmp_eq_u32_e64 s[2:3], s83, v204
	v_cmp_eq_u32_e64 s[72:73], s83, v205
	v_cmp_eq_u32_e64 s[74:75], s83, v206
	v_add_u32_e32 v241, 0x100, v231
	v_add_u32_e32 v242, 0x101, v231
	v_add_u32_e32 v243, 0x102, v231
	v_add_u32_e32 v248, 0x103, v231
	s_mov_b64 exec, s[0:1]
	ds_write2_b32 v240, v241, v6 offset1:1
	v_add_u32_e32 v240, 8, v240
	s_mov_b64 exec, s[2:3]
	ds_write2_b32 v240, v242, v7 offset1:1
	v_add_u32_e32 v240, 8, v240
	s_mov_b64 exec, s[72:73]
	ds_write2_b32 v240, v243, v8 offset1:1
	v_add_u32_e32 v240, 8, v240
	s_mov_b64 exec, s[74:75]
	ds_write2_b32 v240, v248, v9 offset1:1
	v_add_u32_e32 v240, 8, v240
	s_mov_b64 exec, -1
	s_cmpk_lt_u32 s6, 2
	s_cbranch_scc1 .Lsel_W2_done
	v_cmp_eq_u32_e64 s[0:1], s83, v207
	v_cmp_eq_u32_e64 s[2:3], s83, v208
	v_cmp_eq_u32_e64 s[72:73], s83, v209
	v_cmp_eq_u32_e64 s[74:75], s83, v210
	v_add_u32_e32 v241, 0x200, v231
	v_add_u32_e32 v242, 0x201, v231
	v_add_u32_e32 v243, 0x202, v231
	v_add_u32_e32 v248, 0x203, v231
	s_mov_b64 exec, s[0:1]
	ds_write2_b32 v240, v241, v10 offset1:1
	v_add_u32_e32 v240, 8, v240
	s_mov_b64 exec, s[2:3]
	ds_write2_b32 v240, v242, v11 offset1:1
	v_add_u32_e32 v240, 8, v240
	s_mov_b64 exec, s[72:73]
	ds_write2_b32 v240, v243, v12 offset1:1
	v_add_u32_e32 v240, 8, v240
	s_mov_b64 exec, s[74:75]
	ds_write2_b32 v240, v248, v13 offset1:1
	v_add_u32_e32 v240, 8, v240
	s_mov_b64 exec, -1
	s_cmpk_lt_u32 s6, 3
	s_cbranch_scc1 .Lsel_W2_done
	v_cmp_eq_u32_e64 s[0:1], s83, v211
	v_cmp_eq_u32_e64 s[2:3], s83, v212
	v_cmp_eq_u32_e64 s[72:73], s83, v213
	v_cmp_eq_u32_e64 s[74:75], s83, v214
	v_add_u32_e32 v241, 0x300, v231
	v_add_u32_e32 v242, 0x301, v231
	v_add_u32_e32 v243, 0x302, v231
	v_add_u32_e32 v248, 0x303, v231
	s_mov_b64 exec, s[0:1]
	ds_write2_b32 v240, v241, v14 offset1:1
	v_add_u32_e32 v240, 8, v240
	s_mov_b64 exec, s[2:3]
	ds_write2_b32 v240, v242, v15 offset1:1
	v_add_u32_e32 v240, 8, v240
	s_mov_b64 exec, s[72:73]
	ds_write2_b32 v240, v243, v16 offset1:1
	v_add_u32_e32 v240, 8, v240
	s_mov_b64 exec, s[74:75]
	ds_write2_b32 v240, v248, v17 offset1:1
	v_add_u32_e32 v240, 8, v240
	s_mov_b64 exec, -1
	s_cmpk_lt_u32 s6, 4
	s_cbranch_scc1 .Lsel_W2_done
	v_cmp_eq_u32_e64 s[0:1], s83, v215
	v_cmp_eq_u32_e64 s[2:3], s83, v216
	v_cmp_eq_u32_e64 s[72:73], s83, v217
	v_cmp_eq_u32_e64 s[74:75], s83, v218
	v_add_u32_e32 v241, 0x400, v231
	v_add_u32_e32 v242, 0x401, v231
	v_add_u32_e32 v243, 0x402, v231
	v_add_u32_e32 v248, 0x403, v231
	s_mov_b64 exec, s[0:1]
	ds_write2_b32 v240, v241, v18 offset1:1
	v_add_u32_e32 v240, 8, v240
	s_mov_b64 exec, s[2:3]
	ds_write2_b32 v240, v242, v19 offset1:1
	v_add_u32_e32 v240, 8, v240
	s_mov_b64 exec, s[72:73]
	ds_write2_b32 v240, v243, v20 offset1:1
	v_add_u32_e32 v240, 8, v240
	s_mov_b64 exec, s[74:75]
	ds_write2_b32 v240, v248, v21 offset1:1
	v_add_u32_e32 v240, 8, v240
	s_mov_b64 exec, -1
	s_cmpk_lt_u32 s6, 5
	s_cbranch_scc1 .Lsel_W2_done
	v_cmp_eq_u32_e64 s[0:1], s83, v219
	v_cmp_eq_u32_e64 s[2:3], s83, v220
	v_cmp_eq_u32_e64 s[72:73], s83, v221
	v_cmp_eq_u32_e64 s[74:75], s83, v222
	v_add_u32_e32 v241, 0x500, v231
	v_add_u32_e32 v242, 0x501, v231
	v_add_u32_e32 v243, 0x502, v231
	v_add_u32_e32 v248, 0x503, v231
	s_mov_b64 exec, s[0:1]
	ds_write2_b32 v240, v241, v22 offset1:1
	v_add_u32_e32 v240, 8, v240
	s_mov_b64 exec, s[2:3]
	ds_write2_b32 v240, v242, v23 offset1:1
	v_add_u32_e32 v240, 8, v240
	s_mov_b64 exec, s[72:73]
	ds_write2_b32 v240, v243, v24 offset1:1
	v_add_u32_e32 v240, 8, v240
	s_mov_b64 exec, s[74:75]
	ds_write2_b32 v240, v248, v25 offset1:1
	v_add_u32_e32 v240, 8, v240
	s_mov_b64 exec, -1
	s_cmpk_lt_u32 s6, 6
	s_cbranch_scc1 .Lsel_W2_done
	v_cmp_eq_u32_e64 s[0:1], s83, v223
	v_cmp_eq_u32_e64 s[2:3], s83, v224
	v_cmp_eq_u32_e64 s[72:73], s83, v225
	v_cmp_eq_u32_e64 s[74:75], s83, v226
	v_add_u32_e32 v241, 0x600, v231
	v_add_u32_e32 v242, 0x601, v231
	v_add_u32_e32 v243, 0x602, v231
	v_add_u32_e32 v248, 0x603, v231
	s_mov_b64 exec, s[0:1]
	ds_write2_b32 v240, v241, v26 offset1:1
	v_add_u32_e32 v240, 8, v240
	s_mov_b64 exec, s[2:3]
	ds_write2_b32 v240, v242, v27 offset1:1
	v_add_u32_e32 v240, 8, v240
	s_mov_b64 exec, s[72:73]
	ds_write2_b32 v240, v243, v28 offset1:1
	v_add_u32_e32 v240, 8, v240
	s_mov_b64 exec, s[74:75]
	ds_write2_b32 v240, v248, v29 offset1:1
	v_add_u32_e32 v240, 8, v240
	s_mov_b64 exec, -1
	s_cmpk_lt_u32 s6, 7
	s_cbranch_scc1 .Lsel_W2_done
	v_cmp_eq_u32_e64 s[0:1], s83, v227
	v_cmp_eq_u32_e64 s[2:3], s83, v228
	v_cmp_eq_u32_e64 s[72:73], s83, v229
	v_cmp_eq_u32_e64 s[74:75], s83, v230
	v_add_u32_e32 v241, 0x700, v231
	v_add_u32_e32 v242, 0x701, v231
	v_add_u32_e32 v243, 0x702, v231
	v_add_u32_e32 v248, 0x703, v231
	s_mov_b64 exec, s[0:1]
	ds_write2_b32 v240, v241, v30 offset1:1
	v_add_u32_e32 v240, 8, v240
	s_mov_b64 exec, s[2:3]
	ds_write2_b32 v240, v242, v31 offset1:1
	v_add_u32_e32 v240, 8, v240
	s_mov_b64 exec, s[72:73]
	ds_write2_b32 v240, v243, v32 offset1:1
	v_add_u32_e32 v240, 8, v240
	s_mov_b64 exec, s[74:75]
	ds_write2_b32 v240, v248, v33 offset1:1
	v_add_u32_e32 v240, 8, v240
	s_mov_b64 exec, -1
.Lsel_W2_done:
.Lsel_rk:
	s_waitcnt lgkmcnt(0)
	v_lshl_add_u32 v241, v198, 3, s4
	ds_read_b64 v[242:243], v241
	s_waitcnt lgkmcnt(0)
	v_mov_b32_e32 v248, v242
	v_add_f32_e32 v243, 0, v243
	v_ashrrev_i32_e32 v186, 31, v243
	v_or_b32_e32 v186, 0x80000000, v186
	v_xor_b32_e32 v243, v243, v186
	v_not_b32_e32 v242, v242
	v_cmp_gt_u32_e32 vcc, s82, v198
	v_mov_b32_e32 v36, 0
	v_mov_b32_e32 v187, 0
	v_cndmask_b32_e32 v243, 0, v243, vcc
	v_cndmask_b32_e32 v242, 0, v242, vcc
	s_nop 0
	v_readlane_b32 s72, v242, 0
	v_readlane_b32 s73, v243, 0
	v_readlane_b32 s74, v242, 1
	v_readlane_b32 s75, v243, 1
	v_readlane_b32 s76, v242, 2
	v_readlane_b32 s77, v243, 2
	v_readlane_b32 s78, v242, 3
	v_readlane_b32 s79, v243, 3
	v_cmp_gt_u64_e64 vcc, s[72:73], v[242:243]
	v_cmp_gt_u64_e64 s[0:1], s[74:75], v[242:243]
	v_cmp_gt_u64_e64 s[2:3], s[76:77], v[242:243]
	v_cmp_gt_u64_e64 s[4:5], s[78:79], v[242:243]
	v_addc_co_u32_e64 v36, vcc, 0, v36, vcc
	v_addc_co_u32_e64 v187, s[0:1], 0, v187, s[0:1]
	v_addc_co_u32_e64 v36, s[2:3], 0, v36, s[2:3]
	v_addc_co_u32_e64 v187, s[4:5], 0, v187, s[4:5]
	s_cmpk_le_u32 s82, 4
	s_cbranch_scc1 .Lsel_rank_done
	v_readlane_b32 s72, v242, 4
	v_readlane_b32 s73, v243, 4
	v_readlane_b32 s74, v242, 5
	v_readlane_b32 s75, v243, 5
	v_readlane_b32 s76, v242, 6
	v_readlane_b32 s77, v243, 6
	v_readlane_b32 s78, v242, 7
	v_readlane_b32 s79, v243, 7
	v_cmp_gt_u64_e64 vcc, s[72:73], v[242:243]
	v_cmp_gt_u64_e64 s[0:1], s[74:75], v[242:243]
	v_cmp_gt_u64_e64 s[2:3], s[76:77], v[242:243]
	v_cmp_gt_u64_e64 s[4:5], s[78:79], v[242:243]
	v_addc_co_u32_e64 v36, vcc, 0, v36, vcc
	v_addc_co_u32_e64 v187, s[0:1], 0, v187, s[0:1]
	v_addc_co_u32_e64 v36, s[2:3], 0, v36, s[2:3]
	v_addc_co_u32_e64 v187, s[4:5], 0, v187, s[4:5]
	s_cmpk_le_u32 s82, 8
	s_cbranch_scc1 .Lsel_rank_done
	v_readlane_b32 s72, v242, 8
	v_readlane_b32 s73, v243, 8
	v_readlane_b32 s74, v242, 9
	v_readlane_b32 s75, v243, 9
	v_readlane_b32 s76, v242, 10
	v_readlane_b32 s77, v243, 10
	v_readlane_b32 s78, v242, 11
	v_readlane_b32 s79, v243, 11
	v_cmp_gt_u64_e64 vcc, s[72:73], v[242:243]
	v_cmp_gt_u64_e64 s[0:1], s[74:75], v[242:243]
	v_cmp_gt_u64_e64 s[2:3], s[76:77], v[242:243]
	v_cmp_gt_u64_e64 s[4:5], s[78:79], v[242:243]
	v_addc_co_u32_e64 v36, vcc, 0, v36, vcc
	v_addc_co_u32_e64 v187, s[0:1], 0, v187, s[0:1]
	v_addc_co_u32_e64 v36, s[2:3], 0, v36, s[2:3]
	v_addc_co_u32_e64 v187, s[4:5], 0, v187, s[4:5]
	s_cmpk_le_u32 s82, 12
	s_cbranch_scc1 .Lsel_rank_done
	v_readlane_b32 s72, v242, 12
	v_readlane_b32 s73, v243, 12
	v_readlane_b32 s74, v242, 13
	v_readlane_b32 s75, v243, 13
	v_readlane_b32 s76, v242, 14
	v_readlane_b32 s77, v243, 14
	v_readlane_b32 s78, v242, 15
	v_readlane_b32 s79, v243, 15
	v_cmp_gt_u64_e64 vcc, s[72:73], v[242:243]
	v_cmp_gt_u64_e64 s[0:1], s[74:75], v[242:243]
	v_cmp_gt_u64_e64 s[2:3], s[76:77], v[242:243]
	v_cmp_gt_u64_e64 s[4:5], s[78:79], v[242:243]
	v_addc_co_u32_e64 v36, vcc, 0, v36, vcc
	v_addc_co_u32_e64 v187, s[0:1], 0, v187, s[0:1]
	v_addc_co_u32_e64 v36, s[2:3], 0, v36, s[2:3]
	v_addc_co_u32_e64 v187, s[4:5], 0, v187, s[4:5]
	s_cmpk_le_u32 s82, 16
	s_cbranch_scc1 .Lsel_rank_done
	v_readlane_b32 s72, v242, 16
	v_readlane_b32 s73, v243, 16
	v_readlane_b32 s74, v242, 17
	v_readlane_b32 s75, v243, 17
	v_readlane_b32 s76, v242, 18
	v_readlane_b32 s77, v243, 18
	v_readlane_b32 s78, v242, 19
	v_readlane_b32 s79, v243, 19
	v_cmp_gt_u64_e64 vcc, s[72:73], v[242:243]
	v_cmp_gt_u64_e64 s[0:1], s[74:75], v[242:243]
	v_cmp_gt_u64_e64 s[2:3], s[76:77], v[242:243]
	v_cmp_gt_u64_e64 s[4:5], s[78:79], v[242:243]
	v_addc_co_u32_e64 v36, vcc, 0, v36, vcc
	v_addc_co_u32_e64 v187, s[0:1], 0, v187, s[0:1]
	v_addc_co_u32_e64 v36, s[2:3], 0, v36, s[2:3]
	v_addc_co_u32_e64 v187, s[4:5], 0, v187, s[4:5]
	s_cmpk_le_u32 s82, 20
	s_cbranch_scc1 .Lsel_rank_done
	v_readlane_b32 s72, v242, 20
	v_readlane_b32 s73, v243, 20
	v_readlane_b32 s74, v242, 21
	v_readlane_b32 s75, v243, 21
	v_readlane_b32 s76, v242, 22
	v_readlane_b32 s77, v243, 22
	v_readlane_b32 s78, v242, 23
	v_readlane_b32 s79, v243, 23
	v_cmp_gt_u64_e64 vcc, s[72:73], v[242:243]
	v_cmp_gt_u64_e64 s[0:1], s[74:75], v[242:243]
	v_cmp_gt_u64_e64 s[2:3], s[76:77], v[242:243]
	v_cmp_gt_u64_e64 s[4:5], s[78:79], v[242:243]
	v_addc_co_u32_e64 v36, vcc, 0, v36, vcc
	v_addc_co_u32_e64 v187, s[0:1], 0, v187, s[0:1]
	v_addc_co_u32_e64 v36, s[2:3], 0, v36, s[2:3]
	v_addc_co_u32_e64 v187, s[4:5], 0, v187, s[4:5]
	s_cmpk_le_u32 s82, 24
	s_cbranch_scc1 .Lsel_rank_done
	v_readlane_b32 s72, v242, 24
	v_readlane_b32 s73, v243, 24
	v_readlane_b32 s74, v242, 25
	v_readlane_b32 s75, v243, 25
	v_readlane_b32 s76, v242, 26
	v_readlane_b32 s77, v243, 26
	v_readlane_b32 s78, v242, 27
	v_readlane_b32 s79, v243, 27
	v_cmp_gt_u64_e64 vcc, s[72:73], v[242:243]
	v_cmp_gt_u64_e64 s[0:1], s[74:75], v[242:243]
	v_cmp_gt_u64_e64 s[2:3], s[76:77], v[242:243]
	v_cmp_gt_u64_e64 s[4:5], s[78:79], v[242:243]
	v_addc_co_u32_e64 v36, vcc, 0, v36, vcc
	v_addc_co_u32_e64 v187, s[0:1], 0, v187, s[0:1]
	v_addc_co_u32_e64 v36, s[2:3], 0, v36, s[2:3]
	v_addc_co_u32_e64 v187, s[4:5], 0, v187, s[4:5]
	s_cmpk_le_u32 s82, 28
	s_cbranch_scc1 .Lsel_rank_done
	v_readlane_b32 s72, v242, 28
	v_readlane_b32 s73, v243, 28
	v_readlane_b32 s74, v242, 29
	v_readlane_b32 s75, v243, 29
	v_readlane_b32 s76, v242, 30
	v_readlane_b32 s77, v243, 30
	v_readlane_b32 s78, v242, 31
	v_readlane_b32 s79, v243, 31
	v_cmp_gt_u64_e64 vcc, s[72:73], v[242:243]
	v_cmp_gt_u64_e64 s[0:1], s[74:75], v[242:243]
	v_cmp_gt_u64_e64 s[2:3], s[76:77], v[242:243]
	v_cmp_gt_u64_e64 s[4:5], s[78:79], v[242:243]
	v_addc_co_u32_e64 v36, vcc, 0, v36, vcc
	v_addc_co_u32_e64 v187, s[0:1], 0, v187, s[0:1]
	v_addc_co_u32_e64 v36, s[2:3], 0, v36, s[2:3]
	v_addc_co_u32_e64 v187, s[4:5], 0, v187, s[4:5]
	s_cmpk_le_u32 s82, 32
	s_cbranch_scc1 .Lsel_rank_done
	v_readlane_b32 s72, v242, 32
	v_readlane_b32 s73, v243, 32
	v_readlane_b32 s74, v242, 33
	v_readlane_b32 s75, v243, 33
	v_readlane_b32 s76, v242, 34
	v_readlane_b32 s77, v243, 34
	v_readlane_b32 s78, v242, 35
	v_readlane_b32 s79, v243, 35
	v_cmp_gt_u64_e64 vcc, s[72:73], v[242:243]
	v_cmp_gt_u64_e64 s[0:1], s[74:75], v[242:243]
	v_cmp_gt_u64_e64 s[2:3], s[76:77], v[242:243]
	v_cmp_gt_u64_e64 s[4:5], s[78:79], v[242:243]
	v_addc_co_u32_e64 v36, vcc, 0, v36, vcc
	v_addc_co_u32_e64 v187, s[0:1], 0, v187, s[0:1]
	v_addc_co_u32_e64 v36, s[2:3], 0, v36, s[2:3]
	v_addc_co_u32_e64 v187, s[4:5], 0, v187, s[4:5]
	s_cmpk_le_u32 s82, 36
	s_cbranch_scc1 .Lsel_rank_done
	v_readlane_b32 s72, v242, 36
	v_readlane_b32 s73, v243, 36
	v_readlane_b32 s74, v242, 37
	v_readlane_b32 s75, v243, 37
	v_readlane_b32 s76, v242, 38
	v_readlane_b32 s77, v243, 38
	v_readlane_b32 s78, v242, 39
	v_readlane_b32 s79, v243, 39
	v_cmp_gt_u64_e64 vcc, s[72:73], v[242:243]
	v_cmp_gt_u64_e64 s[0:1], s[74:75], v[242:243]
	v_cmp_gt_u64_e64 s[2:3], s[76:77], v[242:243]
	v_cmp_gt_u64_e64 s[4:5], s[78:79], v[242:243]
	v_addc_co_u32_e64 v36, vcc, 0, v36, vcc
	v_addc_co_u32_e64 v187, s[0:1], 0, v187, s[0:1]
	v_addc_co_u32_e64 v36, s[2:3], 0, v36, s[2:3]
	v_addc_co_u32_e64 v187, s[4:5], 0, v187, s[4:5]
	s_cmpk_le_u32 s82, 40
	s_cbranch_scc1 .Lsel_rank_done
	v_readlane_b32 s72, v242, 40
	v_readlane_b32 s73, v243, 40
	v_readlane_b32 s74, v242, 41
	v_readlane_b32 s75, v243, 41
	v_readlane_b32 s76, v242, 42
	v_readlane_b32 s77, v243, 42
	v_readlane_b32 s78, v242, 43
	v_readlane_b32 s79, v243, 43
	v_cmp_gt_u64_e64 vcc, s[72:73], v[242:243]
	v_cmp_gt_u64_e64 s[0:1], s[74:75], v[242:243]
	v_cmp_gt_u64_e64 s[2:3], s[76:77], v[242:243]
	v_cmp_gt_u64_e64 s[4:5], s[78:79], v[242:243]
	v_addc_co_u32_e64 v36, vcc, 0, v36, vcc
	v_addc_co_u32_e64 v187, s[0:1], 0, v187, s[0:1]
	v_addc_co_u32_e64 v36, s[2:3], 0, v36, s[2:3]
	v_addc_co_u32_e64 v187, s[4:5], 0, v187, s[4:5]
	s_cmpk_le_u32 s82, 44
	s_cbranch_scc1 .Lsel_rank_done
	v_readlane_b32 s72, v242, 44
	v_readlane_b32 s73, v243, 44
	v_readlane_b32 s74, v242, 45
	v_readlane_b32 s75, v243, 45
	v_readlane_b32 s76, v242, 46
	v_readlane_b32 s77, v243, 46
	v_readlane_b32 s78, v242, 47
	v_readlane_b32 s79, v243, 47
	v_cmp_gt_u64_e64 vcc, s[72:73], v[242:243]
	v_cmp_gt_u64_e64 s[0:1], s[74:75], v[242:243]
	v_cmp_gt_u64_e64 s[2:3], s[76:77], v[242:243]
	v_cmp_gt_u64_e64 s[4:5], s[78:79], v[242:243]
	v_addc_co_u32_e64 v36, vcc, 0, v36, vcc
	v_addc_co_u32_e64 v187, s[0:1], 0, v187, s[0:1]
	v_addc_co_u32_e64 v36, s[2:3], 0, v36, s[2:3]
	v_addc_co_u32_e64 v187, s[4:5], 0, v187, s[4:5]
	s_cmpk_le_u32 s82, 48
	s_cbranch_scc1 .Lsel_rank_done
	v_readlane_b32 s72, v242, 48
	v_readlane_b32 s73, v243, 48
	v_readlane_b32 s74, v242, 49
	v_readlane_b32 s75, v243, 49
	v_readlane_b32 s76, v242, 50
	v_readlane_b32 s77, v243, 50
	v_readlane_b32 s78, v242, 51
	v_readlane_b32 s79, v243, 51
	v_cmp_gt_u64_e64 vcc, s[72:73], v[242:243]
	v_cmp_gt_u64_e64 s[0:1], s[74:75], v[242:243]
	v_cmp_gt_u64_e64 s[2:3], s[76:77], v[242:243]
	v_cmp_gt_u64_e64 s[4:5], s[78:79], v[242:243]
	v_addc_co_u32_e64 v36, vcc, 0, v36, vcc
	v_addc_co_u32_e64 v187, s[0:1], 0, v187, s[0:1]
	v_addc_co_u32_e64 v36, s[2:3], 0, v36, s[2:3]
	v_addc_co_u32_e64 v187, s[4:5], 0, v187, s[4:5]
	s_cmpk_le_u32 s82, 52
	s_cbranch_scc1 .Lsel_rank_done
	v_readlane_b32 s72, v242, 52
	v_readlane_b32 s73, v243, 52
	v_readlane_b32 s74, v242, 53
	v_readlane_b32 s75, v243, 53
	v_readlane_b32 s76, v242, 54
	v_readlane_b32 s77, v243, 54
	v_readlane_b32 s78, v242, 55
	v_readlane_b32 s79, v243, 55
	v_cmp_gt_u64_e64 vcc, s[72:73], v[242:243]
	v_cmp_gt_u64_e64 s[0:1], s[74:75], v[242:243]
	v_cmp_gt_u64_e64 s[2:3], s[76:77], v[242:243]
	v_cmp_gt_u64_e64 s[4:5], s[78:79], v[242:243]
	v_addc_co_u32_e64 v36, vcc, 0, v36, vcc
	v_addc_co_u32_e64 v187, s[0:1], 0, v187, s[0:1]
	v_addc_co_u32_e64 v36, s[2:3], 0, v36, s[2:3]
	v_addc_co_u32_e64 v187, s[4:5], 0, v187, s[4:5]
	s_cmpk_le_u32 s82, 56
	s_cbranch_scc1 .Lsel_rank_done
	v_readlane_b32 s72, v242, 56
	v_readlane_b32 s73, v243, 56
	v_readlane_b32 s74, v242, 57
	v_readlane_b32 s75, v243, 57
	v_readlane_b32 s76, v242, 58
	v_readlane_b32 s77, v243, 58
	v_readlane_b32 s78, v242, 59
	v_readlane_b32 s79, v243, 59
	v_cmp_gt_u64_e64 vcc, s[72:73], v[242:243]
	v_cmp_gt_u64_e64 s[0:1], s[74:75], v[242:243]
	v_cmp_gt_u64_e64 s[2:3], s[76:77], v[242:243]
	v_cmp_gt_u64_e64 s[4:5], s[78:79], v[242:243]
	v_addc_co_u32_e64 v36, vcc, 0, v36, vcc
	v_addc_co_u32_e64 v187, s[0:1], 0, v187, s[0:1]
	v_addc_co_u32_e64 v36, s[2:3], 0, v36, s[2:3]
	v_addc_co_u32_e64 v187, s[4:5], 0, v187, s[4:5]
	s_cmpk_le_u32 s82, 60
	s_cbranch_scc1 .Lsel_rank_done
	v_readlane_b32 s72, v242, 60
	v_readlane_b32 s73, v243, 60
	v_readlane_b32 s74, v242, 61
	v_readlane_b32 s75, v243, 61
	v_readlane_b32 s76, v242, 62
	v_readlane_b32 s77, v243, 62
	v_readlane_b32 s78, v242, 63
	v_readlane_b32 s79, v243, 63
	v_cmp_gt_u64_e64 vcc, s[72:73], v[242:243]
	v_cmp_gt_u64_e64 s[0:1], s[74:75], v[242:243]
	v_cmp_gt_u64_e64 s[2:3], s[76:77], v[242:243]
	v_cmp_gt_u64_e64 s[4:5], s[78:79], v[242:243]
	v_addc_co_u32_e64 v36, vcc, 0, v36, vcc
	v_addc_co_u32_e64 v187, s[0:1], 0, v187, s[0:1]
	v_addc_co_u32_e64 v36, s[2:3], 0, v36, s[2:3]
	v_addc_co_u32_e64 v187, s[4:5], 0, v187, s[4:5]
